# FFT pair: the 32 loads of the second input block issued right after the previous barrier (before the spectrum read-out) into radix-pass temporaries, one wait at the conversion
# speedup vs baseline: 1.0029x; 1.0029x over previous
.LBB0_653:
	s_or_b64 exec, exec, s[2:3]
	s_waitcnt lgkmcnt(0)
	s_barrier
	s_add_u32 s98, s16, s30
	s_addc_u32 s99, s17, s31
	v_lshl_add_u64 v[148:149], s[98:99], 0, v[28:29]
	s_or_b32 s100, s28, 1
	s_ashr_i32 s101, s100, 31
	s_lshl_b64 s[100:101], s[100:101], 14
	s_add_u32 s100, s16, s100
	s_addc_u32 s101, s17, s101
	v_lshl_add_u64 v[150:151], s[100:101], 0, v[28:29]
	s_movk_i32 s98, 0x3000
	v_add_co_u32_e32 v152, vcc, s47, v148
	s_nop 1
	v_addc_co_u32_e32 v153, vcc, 0, v149, vcc
	v_add_co_u32_e32 v154, vcc, s79, v148
	s_nop 1
	v_addc_co_u32_e32 v155, vcc, 0, v149, vcc
	v_add_co_u32_e32 v156, vcc, s47, v150
	s_nop 1
	v_addc_co_u32_e32 v157, vcc, 0, v151, vcc
	v_add_co_u32_e32 v158, vcc, s79, v150
	s_nop 1
	v_addc_co_u32_e32 v159, vcc, 0, v151, vcc
	v_add_co_u32_e32 v160, vcc, s98, v148
	s_nop 1
	v_addc_co_u32_e32 v161, vcc, 0, v149, vcc
	v_add_co_u32_e32 v162, vcc, s98, v150
	s_nop 1
	v_addc_co_u32_e32 v163, vcc, 0, v151, vcc
	global_load_ushort v116, v[148:149], off
	global_load_ushort v117, v[150:151], off
	global_load_ushort v118, v[148:149], off offset:1024
	global_load_ushort v119, v[150:151], off offset:1024
	global_load_ushort v120, v[148:149], off offset:2048
	global_load_ushort v121, v[150:151], off offset:2048
	global_load_ushort v122, v[150:151], off offset:3072
	global_load_ushort v123, v[148:149], off offset:3072
	global_load_ushort v124, v[152:153], off offset:1024
	global_load_ushort v125, v[152:153], off offset:2048
	global_load_ushort v126, v[154:155], off offset:-4096
	global_load_ushort v127, v[154:155], off
	global_load_ushort v128, v[158:159], off offset:-4096
	global_load_ushort v129, v[154:155], off offset:1024
	global_load_ushort v130, v[154:155], off offset:2048
	global_load_ushort v131, v[156:157], off offset:1024
	global_load_ushort v132, v[156:157], off offset:2048
	global_load_ushort v133, v[156:157], off offset:3072
	global_load_ushort v134, v[160:161], off
	global_load_ushort v135, v[160:161], off offset:1024
	global_load_ushort v136, v[152:153], off offset:3072
	global_load_ushort v137, v[158:159], off
	global_load_ushort v138, v[158:159], off offset:1024
	global_load_ushort v139, v[158:159], off offset:2048
	global_load_ushort v140, v[158:159], off offset:3072
	global_load_ushort v141, v[154:155], off offset:3072
	global_load_ushort v142, v[162:163], off
	global_load_ushort v143, v[162:163], off offset:1024
	global_load_ushort v144, v[160:161], off offset:2048
	global_load_ushort v145, v[162:163], off offset:2048
	global_load_ushort v146, v[162:163], off offset:3072
	global_load_ushort v147, v[160:161], off offset:3072
	s_and_saveexec_b64 s[2:3], s[4:5]
	s_cbranch_execz .LBB0_659
	v_mov_b32_e32 v2, v24
	s_mov_b64 s[10:11], exec
	v_readlane_b32 s12, v253, 7
	v_readlane_b32 s13, v253, 8
	s_and_b64 s[12:13], s[10:11], s[12:13]
	s_mov_b64 exec, s[12:13]
	s_cbranch_execz .LBB0_656
	ds_read_b64 v[2:3], v108
	ds_read_b64 v[20:21], v109
	s_waitcnt lgkmcnt(0)
	v_pk_add_f32 v[30:31], v[2:3], v[20:21]
	v_pk_add_f32 v[2:3], v[2:3], v[20:21] neg_lo:[0,1] neg_hi:[0,1]
	s_nop 0
	v_pk_mov_b32 v[20:21], v[30:31], v[2:3] op_sel:[1,0]
	v_mov_b32_e32 v31, v3
	v_pk_mul_f32 v[22:23], v[20:21], s[48:49]
	v_pk_mul_f32 v[20:21], v[30:31], 0.5 op_sel_hi:[1,0]
	v_mov_b32_e32 v2, v92
	global_store_dwordx4 v[26:27], v[20:23], off

.LBB0_661:
	s_or_b64 exec, exec, s[2:3]
	s_or_b32 s10, s28, 1
	s_add_u32 s30, s16, s30
	s_addc_u32 s31, s17, s31
	v_lshl_add_u64 v[2:3], s[30:31], 0, v[28:29]
	s_ashr_i32 s11, s10, 31
	s_lshl_b64 s[2:3], s[10:11], 14
	v_add_co_u32_e32 v22, vcc, s47, v2
	s_add_u32 s86, s16, s2
	s_nop 0
	v_addc_co_u32_e32 v23, vcc, 0, v3, vcc
	s_addc_u32 s87, s17, s3
	v_add_co_u32_e32 v30, vcc, s79, v2
	v_lshl_add_u64 v[20:21], s[86:87], 0, v[28:29]
	s_nop 0
	v_addc_co_u32_e32 v31, vcc, 0, v3, vcc
	v_add_co_u32_e32 v32, vcc, s47, v20
	s_movk_i32 s2, 0x3000
	s_nop 0
	v_addc_co_u32_e32 v33, vcc, 0, v21, vcc
	v_add_co_u32_e32 v34, vcc, s79, v20
	s_nop 1
	v_addc_co_u32_e32 v35, vcc, 0, v21, vcc
	s_barrier
	s_waitcnt vmcnt(0)
	v_lshlrev_b32_e32 v2, 16, v116
	v_lshlrev_b32_e32 v3, 16, v117
	v_mov_b32_e32 v25, v24
	v_lshlrev_b32_e32 v20, 16, v118
	v_lshlrev_b32_e32 v22, 16, v120
	v_lshlrev_b32_e32 v32, 16, v124
	v_lshlrev_b32_e32 v30, 16, v126
	v_lshlrev_b32_e32 v34, 16, v125
	v_lshlrev_b32_e32 v36, 16, v127
	v_lshlrev_b32_e32 v38, 16, v129
	v_lshlrev_b32_e32 v40, 16, v130
	v_lshlrev_b32_e32 v21, 16, v119
	v_lshlrev_b32_e32 v23, 16, v121
	v_lshlrev_b32_e32 v42, 16, v123
	v_lshlrev_b32_e32 v43, 16, v122
	v_lshlrev_b32_e32 v31, 16, v128
	v_lshlrev_b32_e32 v33, 16, v131
	v_lshlrev_b32_e32 v35, 16, v132
	v_lshlrev_b32_e32 v44, 16, v136
	v_lshlrev_b32_e32 v45, 16, v133
	v_lshlrev_b32_e32 v37, 16, v137
	v_lshlrev_b32_e32 v39, 16, v138
	v_lshlrev_b32_e32 v41, 16, v139
	v_lshlrev_b32_e32 v46, 16, v141
	v_lshlrev_b32_e32 v47, 16, v140
	v_lshlrev_b32_e32 v48, 16, v134
	v_lshlrev_b32_e32 v49, 16, v142
	v_lshlrev_b32_e32 v50, 16, v135
	v_lshlrev_b32_e32 v51, 16, v143
	v_lshlrev_b32_e32 v52, 16, v144
	v_lshlrev_b32_e32 v53, 16, v145
	v_lshlrev_b32_e32 v54, 16, v147
	v_lshlrev_b32_e32 v55, 16, v146
	ds_write_b64 v91, v[2:3]
	ds_write_b64 v93, v[20:21] offset:4096
	ds_write_b64 v94, v[22:23] offset:8192
	ds_write_b64 v95, v[42:43] offset:12288
	ds_write_b64 v96, v[30:31] offset:16384
	ds_write_b64 v97, v[32:33] offset:20480
	ds_write_b64 v98, v[34:35] offset:24576
	ds_write_b64 v99, v[44:45] offset:28672
	ds_write_b64 v100, v[36:37] offset:32768
	ds_write_b64 v101, v[38:39] offset:36864
	ds_write_b64 v102, v[40:41] offset:40960
	ds_write_b64 v103, v[46:47] offset:45056
	ds_write_b64 v104, v[48:49] offset:49152
	ds_write_b64 v105, v[50:51] offset:53248
	ds_write_b64 v106, v[52:53] offset:57344
	ds_write_b64 v107, v[54:55] offset:61440
	s_waitcnt lgkmcnt(0)
	s_barrier
	s_waitcnt vmcnt(0)
	v_lshlrev_b32_e32 v220, 16, v168
	v_and_b32_e32 v221, 0xffff0000, v168
	v_bfe_u32 v222, v218, 16, 1
	v_bfe_u32 v223, v219, 16, 1
	v_add3_u32 v222, v218, v222, v234
	v_add3_u32 v223, v219, v223, v234
	v_lshrrev_b32_e32 v222, 16, v222
	v_and_or_b32 v222, v223, v235, v222
	global_store_dword v[226:227], v222, off
	v_pk_fma_f32 v[218:219], v[186:187], v[218:219], v[220:221]
	v_lshl_add_u64 v[226:227], v[226:227], 0, v[230:231]
	v_lshlrev_b32_e32 v220, 16, v169
	v_and_b32_e32 v221, 0xffff0000, v169
	v_bfe_u32 v222, v218, 16, 1
	v_bfe_u32 v223, v219, 16, 1
	v_add3_u32 v222, v218, v222, v234
	v_add3_u32 v223, v219, v223, v234
	v_lshrrev_b32_e32 v222, 16, v222
	v_and_or_b32 v222, v223, v235, v222
	global_store_dword v[226:227], v222, off
	v_pk_fma_f32 v[218:219], v[188:189], v[218:219], v[220:221]
	v_lshl_add_u64 v[226:227], v[226:227], 0, v[230:231]
	v_lshlrev_b32_e32 v220, 16, v170
	v_and_b32_e32 v221, 0xffff0000, v170
	v_bfe_u32 v222, v218, 16, 1
	v_bfe_u32 v223, v219, 16, 1
	v_add3_u32 v222, v218, v222, v234
	v_add3_u32 v223, v219, v223, v234
	v_lshrrev_b32_e32 v222, 16, v222
	v_and_or_b32 v222, v223, v235, v222
	global_store_dword v[226:227], v222, off
	v_pk_fma_f32 v[218:219], v[190:191], v[218:219], v[220:221]
	v_lshl_add_u64 v[226:227], v[226:227], 0, v[230:231]
	v_lshlrev_b32_e32 v220, 16, v171
	v_and_b32_e32 v221, 0xffff0000, v171
	v_bfe_u32 v222, v218, 16, 1
	v_bfe_u32 v223, v219, 16, 1
	v_add3_u32 v222, v218, v222, v234
	v_add3_u32 v223, v219, v223, v234
	v_lshrrev_b32_e32 v222, 16, v222
	v_and_or_b32 v222, v223, v235, v222
	global_store_dword v[226:227], v222, off
	v_pk_fma_f32 v[218:219], v[192:193], v[218:219], v[220:221]
	v_lshl_add_u64 v[226:227], v[226:227], 0, v[230:231]
	v_lshlrev_b32_e32 v220, 16, v172
	v_and_b32_e32 v221, 0xffff0000, v172
	v_bfe_u32 v222, v218, 16, 1
	v_bfe_u32 v223, v219, 16, 1
	v_add3_u32 v222, v218, v222, v234
	v_add3_u32 v223, v219, v223, v234
	v_lshrrev_b32_e32 v222, 16, v222
	v_and_or_b32 v222, v223, v235, v222
	global_store_dword v[226:227], v222, off
	v_pk_fma_f32 v[218:219], v[194:195], v[218:219], v[220:221]
	v_lshl_add_u64 v[226:227], v[226:227], 0, v[230:231]
	v_lshlrev_b32_e32 v220, 16, v173
	v_and_b32_e32 v221, 0xffff0000, v173
	v_bfe_u32 v222, v218, 16, 1
	v_bfe_u32 v223, v219, 16, 1
	v_add3_u32 v222, v218, v222, v234
	v_add3_u32 v223, v219, v223, v234
	v_lshrrev_b32_e32 v222, 16, v222
	v_and_or_b32 v222, v223, v235, v222
	global_store_dword v[226:227], v222, off
	v_pk_fma_f32 v[218:219], v[196:197], v[218:219], v[220:221]
	v_lshl_add_u64 v[226:227], v[226:227], 0, v[230:231]
	v_lshlrev_b32_e32 v220, 16, v174
	v_and_b32_e32 v221, 0xffff0000, v174
	v_bfe_u32 v222, v218, 16, 1
	v_bfe_u32 v223, v219, 16, 1
	v_add3_u32 v222, v218, v222, v234
	v_add3_u32 v223, v219, v223, v234
	v_lshrrev_b32_e32 v222, 16, v222
	v_and_or_b32 v222, v223, v235, v222
	global_store_dword v[226:227], v222, off
	v_pk_fma_f32 v[218:219], v[198:199], v[218:219], v[220:221]
	v_lshl_add_u64 v[226:227], v[226:227], 0, v[230:231]
	v_lshlrev_b32_e32 v220, 16, v175
	v_and_b32_e32 v221, 0xffff0000, v175
	v_bfe_u32 v222, v218, 16, 1
	v_bfe_u32 v223, v219, 16, 1
	v_add3_u32 v222, v218, v222, v234
	v_add3_u32 v223, v219, v223, v234
	v_lshrrev_b32_e32 v222, 16, v222
	v_and_or_b32 v222, v223, v235, v222
	global_store_dword v[226:227], v222, off
	v_pk_fma_f32 v[218:219], v[200:201], v[218:219], v[220:221]
	v_lshl_add_u64 v[226:227], v[226:227], 0, v[230:231]
	v_lshlrev_b32_e32 v220, 16, v176
	v_and_b32_e32 v221, 0xffff0000, v176
	v_bfe_u32 v222, v218, 16, 1
	v_bfe_u32 v223, v219, 16, 1
	v_add3_u32 v222, v218, v222, v234
	v_add3_u32 v223, v219, v223, v234
	v_lshrrev_b32_e32 v222, 16, v222
	v_and_or_b32 v222, v223, v235, v222
	global_store_dword v[226:227], v222, off
	v_pk_fma_f32 v[218:219], v[202:203], v[218:219], v[220:221]
	v_lshl_add_u64 v[226:227], v[226:227], 0, v[230:231]
	v_lshlrev_b32_e32 v220, 16, v177
	v_and_b32_e32 v221, 0xffff0000, v177
	v_bfe_u32 v222, v218, 16, 1
	v_bfe_u32 v223, v219, 16, 1
	v_add3_u32 v222, v218, v222, v234
	v_add3_u32 v223, v219, v223, v234
	v_lshrrev_b32_e32 v222, 16, v222
	v_and_or_b32 v222, v223, v235, v222
	global_store_dword v[226:227], v222, off
	v_pk_fma_f32 v[218:219], v[204:205], v[218:219], v[220:221]
	v_lshl_add_u64 v[226:227], v[226:227], 0, v[230:231]
	v_lshlrev_b32_e32 v220, 16, v180
	v_and_b32_e32 v221, 0xffff0000, v180
	v_bfe_u32 v222, v218, 16, 1
	v_bfe_u32 v223, v219, 16, 1
	v_add3_u32 v222, v218, v222, v234
	v_add3_u32 v223, v219, v223, v234
	v_lshrrev_b32_e32 v222, 16, v222
	v_and_or_b32 v222, v223, v235, v222
	global_store_dword v[226:227], v222, off
	v_pk_fma_f32 v[218:219], v[206:207], v[218:219], v[220:221]
	v_lshl_add_u64 v[226:227], v[226:227], 0, v[230:231]
	v_lshlrev_b32_e32 v220, 16, v181
	v_and_b32_e32 v221, 0xffff0000, v181
	v_bfe_u32 v222, v218, 16, 1
	v_bfe_u32 v223, v219, 16, 1
	v_add3_u32 v222, v218, v222, v234
	v_add3_u32 v223, v219, v223, v234
	v_lshrrev_b32_e32 v222, 16, v222
	v_and_or_b32 v222, v223, v235, v222
	global_store_dword v[226:227], v222, off
	v_pk_fma_f32 v[218:219], v[208:209], v[218:219], v[220:221]
	v_lshl_add_u64 v[226:227], v[226:227], 0, v[230:231]
	v_lshlrev_b32_e32 v220, 16, v182
	v_and_b32_e32 v221, 0xffff0000, v182
	v_bfe_u32 v222, v218, 16, 1
	v_bfe_u32 v223, v219, 16, 1
	v_add3_u32 v222, v218, v222, v234
	v_add3_u32 v223, v219, v223, v234
	v_lshrrev_b32_e32 v222, 16, v222
	v_and_or_b32 v222, v223, v235, v222
	global_store_dword v[226:227], v222, off
	v_pk_fma_f32 v[218:219], v[210:211], v[218:219], v[220:221]
	v_lshl_add_u64 v[226:227], v[226:227], 0, v[230:231]
	v_lshlrev_b32_e32 v220, 16, v183
	v_and_b32_e32 v221, 0xffff0000, v183
	v_bfe_u32 v222, v218, 16, 1
	v_bfe_u32 v223, v219, 16, 1
	v_add3_u32 v222, v218, v222, v234
	v_add3_u32 v223, v219, v223, v234
	v_lshrrev_b32_e32 v222, 16, v222
	v_and_or_b32 v222, v223, v235, v222
	global_store_dword v[226:227], v222, off
	v_pk_fma_f32 v[218:219], v[212:213], v[218:219], v[220:221]
	v_lshl_add_u64 v[226:227], v[226:227], 0, v[230:231]
	v_lshlrev_b32_e32 v220, 16, v184
	v_and_b32_e32 v221, 0xffff0000, v184
	v_bfe_u32 v222, v218, 16, 1
	v_bfe_u32 v223, v219, 16, 1
	v_add3_u32 v222, v218, v222, v234
	v_add3_u32 v223, v219, v223, v234
	v_lshrrev_b32_e32 v222, 16, v222
	v_and_or_b32 v222, v223, v235, v222
	global_store_dword v[226:227], v222, off
	v_pk_fma_f32 v[218:219], v[214:215], v[218:219], v[220:221]
	v_lshl_add_u64 v[226:227], v[226:227], 0, v[230:231]
	v_lshlrev_b32_e32 v220, 16, v185
	v_and_b32_e32 v221, 0xffff0000, v185
	v_bfe_u32 v222, v218, 16, 1
	v_bfe_u32 v223, v219, 16, 1
	v_add3_u32 v222, v218, v222, v234
	v_add3_u32 v223, v219, v223, v234
	v_lshrrev_b32_e32 v222, 16, v222
	v_and_or_b32 v222, v223, v235, v222
	global_store_dword v[226:227], v222, off
	v_pk_fma_f32 v[218:219], v[216:217], v[218:219], v[220:221]
	v_lshl_add_u64 v[226:227], v[226:227], 0, v[230:231]
	s_nop 0
	global_load_dword v168, v[224:225], off
	global_load_dwordx2 v[186:187], v[228:229], off
	v_lshl_add_u64 v[224:225], v[224:225], 0, v[230:231]
	v_lshl_add_u64 v[228:229], v[228:229], 0, v[232:233]
	global_load_dword v169, v[224:225], off
	global_load_dwordx2 v[188:189], v[228:229], off
	v_lshl_add_u64 v[224:225], v[224:225], 0, v[230:231]
	v_lshl_add_u64 v[228:229], v[228:229], 0, v[232:233]
	global_load_dword v170, v[224:225], off
	global_load_dwordx2 v[190:191], v[228:229], off
	v_lshl_add_u64 v[224:225], v[224:225], 0, v[230:231]
	v_lshl_add_u64 v[228:229], v[228:229], 0, v[232:233]
	global_load_dword v171, v[224:225], off
	global_load_dwordx2 v[192:193], v[228:229], off
	v_lshl_add_u64 v[224:225], v[224:225], 0, v[230:231]
	v_lshl_add_u64 v[228:229], v[228:229], 0, v[232:233]
	global_load_dword v172, v[224:225], off
	global_load_dwordx2 v[194:195], v[228:229], off
	v_lshl_add_u64 v[224:225], v[224:225], 0, v[230:231]
	v_lshl_add_u64 v[228:229], v[228:229], 0, v[232:233]
	global_load_dword v173, v[224:225], off
	global_load_dwordx2 v[196:197], v[228:229], off
	v_lshl_add_u64 v[224:225], v[224:225], 0, v[230:231]
	v_lshl_add_u64 v[228:229], v[228:229], 0, v[232:233]
	global_load_dword v174, v[224:225], off
	global_load_dwordx2 v[198:199], v[228:229], off
	v_lshl_add_u64 v[224:225], v[224:225], 0, v[230:231]
	v_lshl_add_u64 v[228:229], v[228:229], 0, v[232:233]
	global_load_dword v175, v[224:225], off
	global_load_dwordx2 v[200:201], v[228:229], off
	v_lshl_add_u64 v[224:225], v[224:225], 0, v[230:231]
	v_lshl_add_u64 v[228:229], v[228:229], 0, v[232:233]
	global_load_dword v176, v[224:225], off
	global_load_dwordx2 v[202:203], v[228:229], off
	v_lshl_add_u64 v[224:225], v[224:225], 0, v[230:231]
	v_lshl_add_u64 v[228:229], v[228:229], 0, v[232:233]
	global_load_dword v177, v[224:225], off
	global_load_dwordx2 v[204:205], v[228:229], off
	v_lshl_add_u64 v[224:225], v[224:225], 0, v[230:231]
	v_lshl_add_u64 v[228:229], v[228:229], 0, v[232:233]
	global_load_dword v180, v[224:225], off
	global_load_dwordx2 v[206:207], v[228:229], off
	v_lshl_add_u64 v[224:225], v[224:225], 0, v[230:231]
	v_lshl_add_u64 v[228:229], v[228:229], 0, v[232:233]
	global_load_dword v181, v[224:225], off
	global_load_dwordx2 v[208:209], v[228:229], off
	v_lshl_add_u64 v[224:225], v[224:225], 0, v[230:231]
	v_lshl_add_u64 v[228:229], v[228:229], 0, v[232:233]
	global_load_dword v182, v[224:225], off
	global_load_dwordx2 v[210:211], v[228:229], off
	v_lshl_add_u64 v[224:225], v[224:225], 0, v[230:231]
	v_lshl_add_u64 v[228:229], v[228:229], 0, v[232:233]
	global_load_dword v183, v[224:225], off
	global_load_dwordx2 v[212:213], v[228:229], off
	v_lshl_add_u64 v[224:225], v[224:225], 0, v[230:231]
	v_lshl_add_u64 v[228:229], v[228:229], 0, v[232:233]
	global_load_dword v184, v[224:225], off
	global_load_dwordx2 v[214:215], v[228:229], off
	v_lshl_add_u64 v[224:225], v[224:225], 0, v[230:231]
	v_lshl_add_u64 v[228:229], v[228:229], 0, v[232:233]
	global_load_dword v185, v[224:225], off
	global_load_dwordx2 v[216:217], v[228:229], off
	v_lshl_add_u64 v[224:225], v[224:225], 0, v[230:231]
	v_lshl_add_u64 v[228:229], v[228:229], 0, v[232:233]
	s_nop 0
	v_cmp_gt_i32_e32 vcc, s95, v25
	s_and_saveexec_b64 s[2:3], vcc
	s_cbranch_execz .LBB0_664
	v_lshlrev_b32_e32 v0, 4, v25
	s_mov_b64 s[12:13], 0
